# MLA loop: running-max chain and in-place score rescales moved into the PV MFMA block, on top of the counted-wait version
# baseline (speedup 1.0000x reference)
; __device__ __forceinline__ void finishSM(f32x16& p0, f32x16& p1, float alpha, float& l_reg, bf16x8& pa0, bf16x8& pa1, bf16x8& pa2, bf16x8& pa3) {
; #pragma unroll
;     for (int r = 0; r < 16; ++r) p1[r] = __builtin_amdgcn_exp2f(p1[r]);
;     float ps = 0;
; #pragma unroll
;     for (int r = 0; r < 16; ++r) ps += p0[r];
; #pragma unroll
;     for (int r = 0; r < 16; ++r) ps += p1[r];
;     { auto rr = __builtin_amdgcn_permlane32_swap(__float_as_uint(ps), __float_as_uint(ps), false, false);
;       ps = __uint_as_float(rr[0]) + __uint_as_float(rr[1]); }
;     l_reg = l_reg * alpha + ps;
.LBB0_219:
	ds_read_b128 v[64:67], v184 offset:57344
	ds_read_b128 v[68:71], v216 offset:12288
	ds_read_b128 v[222:225], v192 offset:57344
	ds_read_b128 v[226:229], v208 offset:12288
	v_exp_f32_e32 v207, v130
	v_add_f32_e32 v130, 0, v219
	s_waitcnt lgkmcnt(3)
	v_mfma_f32_32x32x16_bf16 v[80:95], v[64:67], v[126:129], 0
	v_add_f32_e32 v130, v221, v130
	v_add_f32_e32 v130, v157, v130
	v_add_f32_e32 v130, v220, v130
	v_add_f32_e32 v130, v156, v130
	v_add_f32_e32 v130, v218, v130
	v_add_f32_e32 v130, v154, v130
	v_add_f32_e32 v130, v155, v130
	s_waitcnt lgkmcnt(2)
	v_mfma_f32_32x32x16_bf16 v[64:79], v[68:71], v[126:129], 0
	v_add_f32_e32 v130, v151, v130
	v_add_f32_e32 v130, v153, v130
	v_add_f32_e32 v130, v150, v130
	v_add_f32_e32 v130, v152, v130
	v_exp_f32_e32 v142, v142
	v_add_f32_e32 v130, v147, v130
	v_exp_f32_e32 v143, v143
	s_waitcnt lgkmcnt(1)
	v_mfma_f32_32x32x16_bf16 v[80:95], v[222:225], v[122:125], v[80:95]
	v_add_f32_e32 v130, v149, v130
	v_exp_f32_e32 v140, v140
	v_add_f32_e32 v130, v146, v130
	v_exp_f32_e32 v141, v141
	v_add_f32_e32 v130, v148, v130
	v_exp_f32_e32 v134, v134
	v_add_f32_e32 v130, v142, v130
	s_waitcnt lgkmcnt(0)
	v_mfma_f32_32x32x16_bf16 v[64:79], v[226:229], v[122:125], v[64:79]
	ds_read_b128 v[222:225], v190 offset:57344
	ds_read_b128 v[226:229], v206 offset:12288
	v_exp_f32_e32 v135, v135
	v_add_f32_e32 v130, v143, v130
	v_exp_f32_e32 v191, v132
	v_add_f32_e32 v130, v140, v130
	v_exp_f32_e32 v205, v133
	v_add_f32_e32 v130, v141, v130
	s_waitcnt lgkmcnt(1)
	v_mfma_f32_32x32x16_bf16 v[80:95], v[222:225], v[118:121], v[80:95]
	v_add_f32_e32 v130, v134, v130
	v_exp_f32_e32 v210, v131
	v_add_f32_e32 v130, v135, v130
	v_exp_f32_e32 v144, v144
	v_add_f32_e32 v130, v191, v130
	v_exp_f32_e32 v145, v145
	v_add_f32_e32 v130, v205, v130
	s_waitcnt lgkmcnt(0)
	v_mfma_f32_32x32x16_bf16 v[64:79], v[226:229], v[118:121], v[64:79]
	ds_read_b128 v[222:225], v173 offset:57344
	ds_read_b128 v[226:229], v202 offset:12288
	v_exp_f32_e32 v138, v138
	v_add_f32_e32 v130, v207, v130
	v_exp_f32_e32 v139, v139
	v_add_f32_e32 v130, v210, v130
	v_exp_f32_e32 v136, v136
	v_add_f32_e32 v130, v144, v130
	s_waitcnt lgkmcnt(1)
	v_mfma_f32_32x32x16_bf16 v[80:95], v[222:225], v[114:117], v[80:95]
	v_exp_f32_e32 v137, v137
	v_add_f32_e32 v130, v145, v130
	v_add_f32_e32 v130, v138, v130
	v_add_f32_e32 v130, v139, v130
	v_add_f32_e32 v130, v136, v130
	s_waitcnt lgkmcnt(0)
	v_mfma_f32_32x32x16_bf16 v[64:79], v[226:229], v[114:117], v[64:79]
	ds_read_b128 v[222:225], v184 offset:57472
	ds_read_b128 v[226:229], v216 offset:12416
	s_waitcnt lgkmcnt(1)
	v_mfma_f32_32x32x16_bf16 v[80:95], v[222:225], v[110:113], v[80:95]
	s_waitcnt lgkmcnt(0)
	v_mfma_f32_32x32x16_bf16 v[64:79], v[226:229], v[110:113], v[64:79]
	ds_read_b128 v[222:225], v192 offset:57472
	ds_read_b128 v[226:229], v208 offset:12416
	s_waitcnt lgkmcnt(1)
	v_mfma_f32_32x32x16_bf16 v[80:95], v[222:225], v[106:109], v[80:95]
	s_waitcnt lgkmcnt(0)
	v_mfma_f32_32x32x16_bf16 v[64:79], v[226:229], v[106:109], v[64:79]
	ds_read_b128 v[222:225], v190 offset:57472
	ds_read_b128 v[226:229], v206 offset:12416
	s_waitcnt lgkmcnt(1)
	v_mfma_f32_32x32x16_bf16 v[80:95], v[222:225], v[102:105], v[80:95]
	s_waitcnt lgkmcnt(0)
	v_mfma_f32_32x32x16_bf16 v[64:79], v[226:229], v[102:105], v[64:79]
	ds_read_b128 v[222:225], v173 offset:57472
	ds_read_b128 v[226:229], v202 offset:12416
	s_waitcnt lgkmcnt(1)
	v_mfma_f32_32x32x16_bf16 v[80:95], v[222:225], v[98:101], v[80:95]
	s_waitcnt lgkmcnt(0)
	v_mfma_f32_32x32x16_bf16 v[64:79], v[226:229], v[98:101], v[64:79]
	ds_read_b128 v[222:225], v184 offset:57600
	ds_read_b128 v[226:229], v216 offset:12544
	ds_read_b128 v[230:233], v181
	s_waitcnt lgkmcnt(0)
	v_mfma_f32_32x32x16_bf16 v[80:95], v[222:225], v[230:233], v[80:95]
	v_mfma_f32_32x32x16_bf16 v[64:79], v[226:229], v[230:233], v[64:79]
	ds_read_b128 v[222:225], v192 offset:57600
	ds_read_b128 v[226:229], v208 offset:12544
	ds_read_b128 v[230:233], v181 offset:8192
	s_waitcnt lgkmcnt(0)
	v_mfma_f32_32x32x16_bf16 v[80:95], v[222:225], v[230:233], v[80:95]
	v_mfma_f32_32x32x16_bf16 v[64:79], v[226:229], v[230:233], v[64:79]
	ds_read_b128 v[222:225], v190 offset:57600
	ds_read_b128 v[226:229], v206 offset:12544
	ds_read_b128 v[230:233], v181 offset:16384
	s_waitcnt lgkmcnt(0)
	v_mfma_f32_32x32x16_bf16 v[80:95], v[222:225], v[230:233], v[80:95]
	v_mfma_f32_32x32x16_bf16 v[64:79], v[226:229], v[230:233], v[64:79]
	ds_read_b128 v[222:225], v173 offset:57600
	ds_read_b128 v[226:229], v202 offset:12544
	ds_read_b128 v[230:233], v181 offset:24576
	s_waitcnt lgkmcnt(0)
; template <int D0> __device__ __forceinline__ void pv_one(f32x16& od, int vb, bf16x8 pa0, bf16x8 pa1, bf16x8 pa2, bf16x8 pa3) {
;     const s16x4 l0 = tr_read<v_rd_off(D0, 0, 0)>(vb), h0 = tr_read<v_rd_off(D0, 0, 1)>(vb), l1 = tr_read<v_rd_off(D0, 1, 0)>(vb), h1 = tr_read<v_rd_off(D0, 1, 1)>(vb);
;     const s16x4 l2 = tr_read<v_rd_off(D0, 2, 0)>(vb), h2 = tr_read<v_rd_off(D0, 2, 1)>(vb), l3 = tr_read<v_rd_off(D0, 3, 0)>(vb), h3 = tr_read<v_rd_off(D0, 3, 1)>(vb);
;     asm volatile("s_waitcnt lgkmcnt(0)" ::: "memory"); SBAR();
;     ...
;     od = __builtin_amdgcn_mfma_f32_32x32x16_bf16(pa0, PK(l0, h0), od, 0, 0, 0);
;     od = __builtin_amdgcn_mfma_f32_32x32x16_bf16(pa1, PK(l1, h1), od, 0, 0, 0);
;     od = __builtin_amdgcn_mfma_f32_32x32x16_bf16(pa2, PK(l2, h2), od, 0, 0, 0);
;     od = __builtin_amdgcn_mfma_f32_32x32x16_bf16(pa3, PK(l3, h3), od, 0, 0, 0);
;     ...
; }
; __device__ __forceinline__ void pv_d0(f32x16* o, int vb, bf16x8 pa0, bf16x8 pa1, bf16x8 pa2, bf16x8 pa3) {
;     pv_one<0>(o[0], vb, pa0, pa1, pa2, pa3); pv_one<1>(o[1], vb, pa0, pa1, pa2, pa3); pv_one<2>(o[2], vb, pa0, pa1, pa2, pa3); pv_one<3>(o[3], vb, pa0, pa1, pa2, pa3);
; }
; __device__ __forceinline__ void partialSM(f32x16& p0, f32x16& p1, float& m_reg, float& mn, float& alpha, const float C, const float thr) {
;     float pmax = p0[0];
; #pragma unroll
;     for (int r = 1; r < 16; ++r) pmax = fmaxf(pmax, p0[r]);
; #pragma unroll
;     for (int r = 0; r < 16; ++r) pmax = fmaxf(pmax, p1[r]);
;     { auto rr = __builtin_amdgcn_permlane32_swap(__float_as_uint(pmax), __float_as_uint(pmax), false, false);
;       pmax = fmaxf(__uint_as_float(rr[0]), __uint_as_float(rr[1])); }
;     if (__builtin_expect(__all(pmax - m_reg <= thr), 1)) { mn = m_reg; alpha = 1.f; }
;     else { mn = fmaxf(m_reg, pmax); alpha = __builtin_amdgcn_exp2f((m_reg - mn) * C); m_reg = mn; }
;     const float mnC = -mn * C;
; #pragma unroll
;     for (int r = 0; r < 16; ++r) p0[r] = fmaf(p0[r], C, mnC);
; #pragma unroll
;     for (int r = 0; r < 16; ++r) p1[r] = fmaf(p1[r], C, mnC);
; #pragma unroll
;     for (int r = 0; r < 16; ++r) p0[r] = __builtin_amdgcn_exp2f(p0[r]);
; }
; __device__ __forceinline__ void finishSM(f32x16& p0, f32x16& p1, float alpha, float& l_reg, bf16x8& pa0, bf16x8& pa1, bf16x8& pa2, bf16x8& pa3) {
; #pragma unroll
;     for (int r = 0; r < 16; ++r) p1[r] = __builtin_amdgcn_exp2f(p1[r]);
;     float ps = 0;
	v_mfma_f32_32x32x16_bf16 v[80:95], v[222:225], v[230:233], v[80:95]
	v_add_f32_e32 v222, v137, v130
	v_mov_b32_e32 v223, v222
	v_cvt_pk_bf16_f32 v130, v219, v221
	v_cvt_pk_bf16_f32 v131, v157, v220
	v_cvt_pk_bf16_f32 v132, v156, v218
	v_cvt_pk_bf16_f32 v133, v154, v155
	v_cvt_pk_bf16_f32 v154, v151, v153
	v_mfma_f32_32x32x16_bf16 v[64:79], v[226:229], v[230:233], v[64:79]
	v_cvt_pk_bf16_f32 v155, v150, v152
	v_cvt_pk_bf16_f32 v156, v147, v149
	v_cvt_pk_bf16_f32 v157, v146, v148
	v_cvt_pk_bf16_f32 v218, v142, v143
	v_cvt_pk_bf16_f32 v219, v140, v141
	v_cvt_pk_bf16_f32 v220, v134, v135
	v_cvt_pk_bf16_f32 v221, v191, v205
	v_cvt_pk_bf16_f32 v224, v207, v210
	v_cvt_pk_bf16_f32 v225, v144, v145
	v_cvt_pk_bf16_f32 v226, v138, v139
	v_cvt_pk_bf16_f32 v227, v136, v137
	s_nop 0
	v_permlane32_swap_b32_e32 v222, v223
	v_permlane32_swap_b32_e32 v130, v132
	v_permlane32_swap_b32_e32 v225, v227
	v_permlane32_swap_b32_e32 v131, v133
	v_permlane32_swap_b32_e32 v154, v156
	v_permlane32_swap_b32_e32 v155, v157
	v_permlane32_swap_b32_e32 v218, v220
	v_permlane32_swap_b32_e32 v219, v221
	v_permlane32_swap_b32_e32 v224, v226
	s_cmp_lt_u32 s69, s68
	s_cselect_b32 s14, 0, s68
	s_cselect_b32 s15, s25, s28
	s_lshl_b32 s14, s14, 6
	s_sub_i32 s14, s15, s14
	s_add_i32 s14, s37, s14
	s_ashr_i32 s15, s14, 31
	v_lshl_add_u64 v[134:135], s[14:15], 0, v[174:175]
	v_lshl_add_u64 v[136:137], v[176:177], 0, s[14:15]
	v_lshlrev_b64 v[134:135], 12, v[134:135]
	v_lshlrev_b64 v[136:137], 12, v[136:137]
	v_lshl_add_u64 v[134:135], v[178:179], 0, v[134:135]
	v_lshl_add_u64 v[138:139], v[178:179], 0, v[136:137]
	v_mad_i64_i32 v[142:143], s[20:21], v164, s14, 0
	v_mad_i64_i32 v[146:147], s[20:21], v168, s14, 0
	v_mad_i64_i32 v[150:151], s[14:15], v172, s14, 0
	global_load_dwordx4 v[134:137], v[134:135], off offset:256
	s_nop 0
	global_load_dwordx4 v[138:141], v[138:139], off offset:256
	v_lshl_add_u64 v[142:143], v[142:143], 1, v[162:163]
	v_lshl_add_u64 v[146:147], v[146:147], 1, v[166:167]
	v_lshl_add_u64 v[150:151], v[150:151], 1, v[170:171]
	global_load_dwordx4 v[142:145], v[142:143], off
	s_nop 0
	global_load_dwordx4 v[146:149], v[146:147], off
	s_nop 0
	global_load_dwordx4 v[150:153], v[150:151], off
	ds_read_b64_tr_b16 v[228:229], v200 offset:0
	ds_read_b64_tr_b16 v[230:231], v200 offset:0x800
	ds_read_b64_tr_b16 v[232:233], v200 offset:0x1000
	ds_read_b64_tr_b16 v[234:235], v200 offset:0x1800
	ds_read_b64_tr_b16 v[236:237], v200 offset:0x2000
	ds_read_b64_tr_b16 v[238:239], v200 offset:0x2800
	ds_read_b64_tr_b16 v[240:241], v200 offset:0x3000
	ds_read_b64_tr_b16 v[242:243], v200 offset:0x3800
	s_waitcnt lgkmcnt(0)
	s_nop 0
	v_mfma_f32_32x32x16_bf16 v[48:63], v[130:133], v[228:231], v[48:63]
	ds_read_b64_tr_b16 v[228:229], v200 offset:0x200
	ds_read_b64_tr_b16 v[230:231], v200 offset:0xa00
	v_max_f32_e32 v248, v81, v81
	v_max_f32_e32 v249, v80, v80
	v_max_f32_e32 v248, v249, v248
	v_max3_f32 v248, v248, v82, v83
	v_max3_f32 v248, v248, v84, v85
	v_max3_f32 v248, v248, v86, v87
	v_mfma_f32_32x32x16_bf16 v[48:63], v[154:157], v[232:235], v[48:63]
	ds_read_b64_tr_b16 v[232:233], v200 offset:0x1200
	ds_read_b64_tr_b16 v[234:235], v200 offset:0x1a00
	v_max3_f32 v248, v248, v88, v89
	v_max3_f32 v248, v248, v90, v91
	v_max3_f32 v248, v248, v92, v93
	v_max3_f32 v248, v248, v94, v95
	v_max3_f32 v248, v248, v64, v65
	v_max3_f32 v248, v248, v66, v67
	v_mfma_f32_32x32x16_bf16 v[48:63], v[218:221], v[236:239], v[48:63]
	ds_read_b64_tr_b16 v[236:237], v200 offset:0x2200
	ds_read_b64_tr_b16 v[238:239], v200 offset:0x2a00
	v_max3_f32 v248, v248, v68, v69
	v_max3_f32 v248, v248, v70, v71
	v_max3_f32 v248, v248, v72, v73
	v_max3_f32 v248, v248, v74, v75
	v_max3_f32 v248, v248, v76, v77
	v_max3_f32 v248, v248, v78, v79
	v_mfma_f32_32x32x16_bf16 v[48:63], v[224:227], v[240:243], v[48:63]
	ds_read_b64_tr_b16 v[240:241], v200 offset:0x3200
	ds_read_b64_tr_b16 v[242:243], v200 offset:0x3a00
	v_mov_b32_e32 v249, v248
	s_nop 1
	v_permlane32_swap_b32_e32 v248, v249
	v_max_f32_e32 v249, v249, v249
	v_max_f32_e32 v248, v248, v248
	v_max_f32_e32 v248, v248, v249
	s_waitcnt lgkmcnt(6)
	v_mfma_f32_32x32x16_bf16 v[32:47], v[130:133], v[228:231], v[32:47]
	ds_read_b64_tr_b16 v[228:229], v200 offset:0x400
	ds_read_b64_tr_b16 v[230:231], v200 offset:0xc00
	v_sub_f32_e32 v249, v248, v204
	v_cmp_ge_f32_e32 vcc, s72, v249
	v_max_f32_e32 v249, v204, v204
	v_max_f32_e32 v248, v249, v248
	v_sub_f32_e32 v249, v204, v248
	v_mul_f32_e32 v249, 0x3dd53b94, v249
	s_waitcnt lgkmcnt(6)
	v_mfma_f32_32x32x16_bf16 v[32:47], v[154:157], v[232:235], v[32:47]
	ds_read_b64_tr_b16 v[232:233], v200 offset:0x1400
	ds_read_b64_tr_b16 v[234:235], v200 offset:0x1c00
	v_exp_f32_e32 v249, v249
	s_cmp_eq_u64 vcc, exec
	s_cselect_b64 s[14:15], -1, 0
	v_cndmask_b32_e64 v250, v249, 1.0, s[14:15]
	v_cmp_gt_f32_e32 vcc, 1.0, v250
	s_waitcnt lgkmcnt(6)
	v_mfma_f32_32x32x16_bf16 v[32:47], v[218:221], v[236:239], v[32:47]
	ds_read_b64_tr_b16 v[236:237], v200 offset:0x2400
	ds_read_b64_tr_b16 v[238:239], v200 offset:0x2c00
	v_cndmask_b32_e64 v251, v248, v204, s[14:15]
	v_mul_f32_e32 v249, 0xbdd53b94, v251
	v_fmamk_f32 v80, v80, 0x3dd53b94, v249
	v_fmamk_f32 v87, v87, 0x3dd53b94, v249
	s_waitcnt lgkmcnt(6)
	v_mfma_f32_32x32x16_bf16 v[32:47], v[224:227], v[240:243], v[32:47]
	ds_read_b64_tr_b16 v[240:241], v200 offset:0x3400
	ds_read_b64_tr_b16 v[242:243], v200 offset:0x3c00
	v_fmamk_f32 v82, v82, 0x3dd53b94, v249
	v_fmamk_f32 v84, v84, 0x3dd53b94, v249
	v_fmamk_f32 v86, v86, 0x3dd53b94, v249
	v_fmamk_f32 v88, v88, 0x3dd53b94, v249
	s_waitcnt lgkmcnt(6)
; __device__ __forceinline__ void partialSM(f32x16& p0, f32x16& p1, float& m_reg, float& mn, float& alpha, const float C, const float thr) {
;     float pmax = p0[0];
; #pragma unroll
;     for (int r = 1; r < 16; ++r) pmax = fmaxf(pmax, p0[r]);
; #pragma unroll
;     for (int r = 0; r < 16; ++r) pmax = fmaxf(pmax, p1[r]);
;     { auto rr = __builtin_amdgcn_permlane32_swap(__float_as_uint(pmax), __float_as_uint(pmax), false, false);
;       pmax = fmaxf(__uint_as_float(rr[0]), __uint_as_float(rr[1])); }
;     if (__builtin_expect(__all(pmax - m_reg <= thr), 1)) { mn = m_reg; alpha = 1.f; }
;     else { mn = fmaxf(m_reg, pmax); alpha = __builtin_amdgcn_exp2f((m_reg - mn) * C); m_reg = mn; }
;     const float mnC = -mn * C;
; #pragma unroll
;     for (int r = 0; r < 16; ++r) p0[r] = fmaf(p0[r], C, mnC);
; #pragma unroll
;     for (int r = 0; r < 16; ++r) p1[r] = fmaf(p1[r], C, mnC);
; #pragma unroll
;     for (int r = 0; r < 16; ++r) p0[r] = __builtin_amdgcn_exp2f(p0[r]);
; }
; __device__ __forceinline__ void finishSM(f32x16& p0, f32x16& p1, float alpha, float& l_reg, bf16x8& pa0, bf16x8& pa1, bf16x8& pa2, bf16x8& pa3) {
; #pragma unroll
;     for (int r = 0; r < 16; ++r) p1[r] = __builtin_amdgcn_exp2f(p1[r]);
	v_mfma_f32_32x32x16_bf16 v[16:31], v[130:133], v[228:231], v[16:31]
	ds_read_b64_tr_b16 v[228:229], v200 offset:0x600
	ds_read_b64_tr_b16 v[230:231], v200 offset:0xe00
	v_fmamk_f32 v90, v90, 0x3dd53b94, v249
	v_fmamk_f32 v92, v92, 0x3dd53b94, v249
	v_fmamk_f32 v94, v94, 0x3dd53b94, v249
	v_fmamk_f32 v81, v81, 0x3dd53b94, v249
	s_waitcnt lgkmcnt(6)
	v_mfma_f32_32x32x16_bf16 v[16:31], v[154:157], v[232:235], v[16:31]
	ds_read_b64_tr_b16 v[232:233], v200 offset:0x1600
	ds_read_b64_tr_b16 v[234:235], v200 offset:0x1e00
	v_fmamk_f32 v83, v83, 0x3dd53b94, v249
	v_fmamk_f32 v85, v85, 0x3dd53b94, v249
	v_fmamk_f32 v89, v89, 0x3dd53b94, v249
	v_fmamk_f32 v91, v91, 0x3dd53b94, v249
	s_waitcnt lgkmcnt(6)
	v_mfma_f32_32x32x16_bf16 v[16:31], v[218:221], v[236:239], v[16:31]
	ds_read_b64_tr_b16 v[236:237], v200 offset:0x2600
	ds_read_b64_tr_b16 v[238:239], v200 offset:0x2e00
	v_fmamk_f32 v93, v93, 0x3dd53b94, v249
	v_fmamk_f32 v95, v95, 0x3dd53b94, v249
	s_waitcnt lgkmcnt(6)
	v_mfma_f32_32x32x16_bf16 v[16:31], v[224:227], v[240:243], v[16:31]
	ds_read_b64_tr_b16 v[240:241], v200 offset:0x3600
	ds_read_b64_tr_b16 v[242:243], v200 offset:0x3e00
	s_waitcnt lgkmcnt(6)
	v_mfma_f32_32x32x16_bf16 v[0:15], v[130:133], v[228:231], v[0:15]
	s_waitcnt lgkmcnt(4)
	v_mfma_f32_32x32x16_bf16 v[0:15], v[154:157], v[232:235], v[0:15]
	s_waitcnt lgkmcnt(2)
	v_mfma_f32_32x32x16_bf16 v[0:15], v[218:221], v[236:239], v[0:15]
	s_waitcnt lgkmcnt(0)
	v_mfma_f32_32x32x16_bf16 v[0:15], v[224:227], v[240:243], v[0:15]
	v_mov_b32_e32 v225, v250
	s_barrier
	s_waitcnt vmcnt(4)
	ds_write_b128 v186, v[134:137]
	s_waitcnt vmcnt(3)
	ds_write_b128 v188, v[138:141]
	s_waitcnt vmcnt(2)
	ds_write_b128 v194, v[142:145] offset:32768
	s_waitcnt vmcnt(1)
	ds_write_b128 v196, v[146:149] offset:32768
	s_waitcnt vmcnt(0)
	ds_write_b128 v198, v[150:153] offset:32768
	s_cbranch_vccz .LBB0_223
	s_and_saveexec_b64 s[20:21], s[12:13]
	ds_write_b32 v165, v225 offset:128
	s_or_b64 exec, exec, s[20:21]
	s_waitcnt lgkmcnt(0)
	v_add_u32_e32 v131, v161, v96
	ds_read_b128 v[132:135], v131 offset:224
	ds_read_b128 v[136:139], v131 offset:192
	ds_read_b128 v[140:143], v131 offset:160
	ds_read_b128 v[144:147], v131 offset:128
	s_waitcnt lgkmcnt(3)
	v_pk_mul_f32 v[60:61], v[60:61], v[132:133]
	s_waitcnt lgkmcnt(2)
	v_pk_mul_f32 v[56:57], v[56:57], v[136:137]
	s_waitcnt lgkmcnt(1)
	v_pk_mul_f32 v[52:53], v[52:53], v[140:141]
	v_pk_mul_f32 v[62:63], v[62:63], v[134:135]
	v_pk_mul_f32 v[58:59], v[58:59], v[138:139]
	v_pk_mul_f32 v[54:55], v[54:55], v[142:143]
	s_waitcnt lgkmcnt(0)
	v_pk_mul_f32 v[50:51], v[50:51], v[146:147]
	v_pk_mul_f32 v[48:49], v[48:49], v[144:145]
	v_pk_mul_f32 v[44:45], v[44:45], v[132:133]
	v_pk_mul_f32 v[40:41], v[40:41], v[136:137]
	v_pk_mul_f32 v[36:37], v[36:37], v[140:141]
	v_pk_mul_f32 v[46:47], v[46:47], v[134:135]
	v_pk_mul_f32 v[42:43], v[42:43], v[138:139]
	v_pk_mul_f32 v[38:39], v[38:39], v[142:143]
	v_pk_mul_f32 v[34:35], v[34:35], v[146:147]
	v_pk_mul_f32 v[32:33], v[32:33], v[144:145]
	v_pk_mul_f32 v[28:29], v[28:29], v[132:133]
	v_pk_mul_f32 v[24:25], v[24:25], v[136:137]
	v_pk_mul_f32 v[20:21], v[20:21], v[140:141]
	v_pk_mul_f32 v[30:31], v[30:31], v[134:135]
	v_pk_mul_f32 v[26:27], v[26:27], v[138:139]
	v_pk_mul_f32 v[22:23], v[22:23], v[142:143]
	v_pk_mul_f32 v[18:19], v[18:19], v[146:147]
	v_pk_mul_f32 v[16:17], v[16:17], v[144:145]
	v_pk_mul_f32 v[12:13], v[12:13], v[132:133]
	v_pk_mul_f32 v[8:9], v[8:9], v[136:137]
	v_pk_mul_f32 v[4:5], v[4:5], v[140:141]
	v_pk_mul_f32 v[14:15], v[14:15], v[134:135]
	v_pk_mul_f32 v[10:11], v[10:11], v[138:139]
	v_pk_mul_f32 v[6:7], v[6:7], v[142:143]
	v_pk_mul_f32 v[2:3], v[2:3], v[146:147]
	v_pk_mul_f32 v[0:1], v[0:1], v[144:145]
.LBB0_223:
	v_cndmask_b32_e64 v204, v248, v204, s[14:15]
	v_mul_f32_e32 v138, 0xbdd53b94, v204
	v_fmamk_f32 v140, v70, 0x3dd53b94, v138
	v_exp_f32_e32 v130, v80
	v_exp_f32_e32 v224, v87
	v_fmamk_f32 v145, v64, 0x3dd53b94, v138
	v_fmamk_f32 v144, v66, 0x3dd53b94, v138
	v_fmamk_f32 v143, v68, 0x3dd53b94, v138
	v_fmamk_f32 v139, v72, 0x3dd53b94, v138
	v_fmamk_f32 v146, v74, 0x3dd53b94, v138
	v_fmamk_f32 v142, v76, 0x3dd53b94, v138
	v_fmamk_f32 v141, v78, 0x3dd53b94, v138
	v_exp_f32_e32 v131, v82
	v_exp_f32_e32 v132, v84
	v_exp_f32_e32 v133, v86
	v_exp_f32_e32 v137, v88
	v_exp_f32_e32 v136, v90
	v_exp_f32_e32 v135, v92
	v_exp_f32_e32 v134, v94
	v_fmamk_f32 v147, v65, 0x3dd53b94, v138
	v_fmamk_f32 v156, v67, 0x3dd53b94, v138
	v_fmamk_f32 v157, v69, 0x3dd53b94, v138
	v_fmamk_f32 v191, v71, 0x3dd53b94, v138
	v_fmamk_f32 v205, v73, 0x3dd53b94, v138
	v_fmamk_f32 v207, v75, 0x3dd53b94, v138
	v_fmamk_f32 v210, v77, 0x3dd53b94, v138
	v_fmac_f32_e32 v138, 0x3dd53b94, v79
	v_exp_f32_e32 v211, v81
	v_exp_f32_e32 v212, v83
	v_exp_f32_e32 v213, v85
	v_exp_f32_e32 v228, v89
	v_exp_f32_e32 v229, v91
	v_exp_f32_e32 v230, v93
	v_exp_f32_e32 v231, v95
	s_waitcnt lgkmcnt(0)
	s_barrier
; __device__ __forceinline__ void finishSM(f32x16& p0, f32x16& p1, float alpha, float& l_reg, bf16x8& pa0, bf16x8& pa1, bf16x8& pa2, bf16x8& pa3) {
; #pragma unroll
;     for (int r = 0; r < 16; ++r) p1[r] = __builtin_amdgcn_exp2f(p1[r]);
;     float ps = 0;
; #pragma unroll
;     for (int r = 0; r < 16; ++r) ps += p0[r];
; #pragma unroll
;     for (int r = 0; r < 16; ++r) ps += p1[r];
;     { auto rr = __builtin_amdgcn_permlane32_swap(__float_as_uint(ps), __float_as_uint(ps), false, false);
;       ps = __uint_as_float(rr[0]) + __uint_as_float(rr[1]); }
;     l_reg = l_reg * alpha + ps;
;     ...
;     PK4(p0, 0, pa0); PK4(p0, 8, pa1); PK4(p1, 0, pa2); PK4(p1, 8, pa3);
	ds_read_b128 v[64:67], v184 offset:32768
	ds_read_b128 v[68:71], v184 offset:45056
	ds_read_b128 v[148:151], v192 offset:32768
	ds_read_b128 v[152:155], v192 offset:45056
	v_exp_f32_e32 v145, v145
	v_exp_f32_e32 v147, v147
	s_waitcnt lgkmcnt(3)
	v_mfma_f32_32x32x16_bf16 v[80:95], v[64:67], v[126:129], 0
	v_exp_f32_e32 v144, v144
	v_exp_f32_e32 v143, v143
	v_exp_f32_e32 v140, v140
	v_exp_f32_e32 v139, v139
	v_exp_f32_e32 v146, v146
	v_exp_f32_e32 v142, v142
	v_exp_f32_e32 v141, v141
	s_waitcnt lgkmcnt(2)
	v_mfma_f32_32x32x16_bf16 v[64:79], v[68:71], v[126:129], 0
	v_exp_f32_e32 v138, v138
	s_waitcnt lgkmcnt(0)
	v_mfma_f32_32x32x16_bf16 v[64:79], v[152:155], v[122:125], v[64:79]
	v_mfma_f32_32x32x16_bf16 v[80:95], v[148:151], v[122:125], v[80:95]
	ds_read_b128 v[148:151], v190 offset:32768
	ds_read_b128 v[152:155], v190 offset:45056
	s_waitcnt lgkmcnt(0)
	v_mfma_f32_32x32x16_bf16 v[64:79], v[152:155], v[118:121], v[64:79]
	v_mfma_f32_32x32x16_bf16 v[80:95], v[148:151], v[118:121], v[80:95]
	ds_read_b128 v[148:151], v173 offset:32768
	ds_read_b128 v[152:155], v173 offset:45056
	s_waitcnt lgkmcnt(0)
	v_mfma_f32_32x32x16_bf16 v[64:79], v[152:155], v[114:117], v[64:79]
	v_mfma_f32_32x32x16_bf16 v[80:95], v[148:151], v[114:117], v[80:95]
	ds_read_b128 v[148:151], v184 offset:32896
	ds_read_b128 v[152:155], v184 offset:45184
	s_waitcnt lgkmcnt(0)
	v_mfma_f32_32x32x16_bf16 v[64:79], v[152:155], v[110:113], v[64:79]
	v_mfma_f32_32x32x16_bf16 v[80:95], v[148:151], v[110:113], v[80:95]
	ds_read_b128 v[148:151], v192 offset:32896
	ds_read_b128 v[152:155], v192 offset:45184
	s_waitcnt lgkmcnt(0)
	v_mfma_f32_32x32x16_bf16 v[64:79], v[152:155], v[106:109], v[64:79]
	v_mfma_f32_32x32x16_bf16 v[80:95], v[148:151], v[106:109], v[80:95]
	ds_read_b128 v[148:151], v190 offset:32896
	ds_read_b128 v[152:155], v190 offset:45184
	s_waitcnt lgkmcnt(0)
	v_mfma_f32_32x32x16_bf16 v[64:79], v[152:155], v[102:105], v[64:79]
	v_mfma_f32_32x32x16_bf16 v[80:95], v[148:151], v[102:105], v[80:95]
	ds_read_b128 v[148:151], v173 offset:32896
	ds_read_b128 v[152:155], v173 offset:45184
	s_waitcnt lgkmcnt(0)
	v_mfma_f32_32x32x16_bf16 v[64:79], v[152:155], v[98:101], v[64:79]
	v_mfma_f32_32x32x16_bf16 v[80:95], v[148:151], v[98:101], v[80:95]
	ds_read_b128 v[148:151], v184 offset:33024
	ds_read_b128 v[152:155], v184 offset:45312
	ds_read_b128 v[218:221], v181
	s_waitcnt lgkmcnt(0)
	v_mfma_f32_32x32x16_bf16 v[64:79], v[152:155], v[218:221], v[64:79]
	v_mfma_f32_32x32x16_bf16 v[80:95], v[148:151], v[218:221], v[80:95]
	ds_read_b128 v[148:151], v192 offset:33024
	ds_read_b128 v[152:155], v192 offset:45312
	ds_read_b128 v[218:221], v181 offset:8192
	s_waitcnt lgkmcnt(0)
	v_mfma_f32_32x32x16_bf16 v[64:79], v[152:155], v[218:221], v[64:79]
	v_mfma_f32_32x32x16_bf16 v[80:95], v[148:151], v[218:221], v[80:95]
	ds_read_b128 v[148:151], v190 offset:33024
	ds_read_b128 v[152:155], v190 offset:45312
	ds_read_b128 v[218:221], v181 offset:16384
	s_waitcnt lgkmcnt(0)
	v_mfma_f32_32x32x16_bf16 v[64:79], v[152:155], v[218:221], v[64:79]
	v_mfma_f32_32x32x16_bf16 v[80:95], v[148:151], v[218:221], v[80:95]
	ds_read_b128 v[148:151], v173 offset:33024
	ds_read_b128 v[152:155], v173 offset:45312
	ds_read_b128 v[218:221], v181 offset:24576
	s_waitcnt lgkmcnt(0)
	v_mfma_f32_32x32x16_bf16 v[64:79], v[152:155], v[218:221], v[64:79]
	v_add_f32_e32 v154, 0, v130
	v_add_f32_e32 v154, v211, v154
	v_add_f32_e32 v154, v131, v154
	v_add_f32_e32 v154, v212, v154
	v_add_f32_e32 v154, v132, v154
	v_add_f32_e32 v154, v213, v154
	v_add_f32_e32 v154, v133, v154
	v_add_f32_e32 v154, v224, v154
	v_add_f32_e32 v154, v137, v154
	v_add_f32_e32 v154, v228, v154
	v_add_f32_e32 v154, v136, v154
	v_add_f32_e32 v154, v229, v154
	v_add_f32_e32 v154, v135, v154
	v_add_f32_e32 v154, v230, v154
	v_add_f32_e32 v154, v134, v154
	v_mfma_f32_32x32x16_bf16 v[80:95], v[148:151], v[218:221], v[80:95]
	v_exp_f32_e32 v148, v156
	v_add_f32_e32 v154, v231, v154
	v_add_f32_e32 v154, v145, v154
	v_exp_f32_e32 v149, v157
	v_add_f32_e32 v154, v147, v154
	v_add_f32_e32 v154, v144, v154
	v_exp_f32_e32 v150, v191
	v_add_f32_e32 v154, v148, v154
	v_add_f32_e32 v154, v143, v154
	v_exp_f32_e32 v151, v205
	v_add_f32_e32 v154, v149, v154
	v_add_f32_e32 v154, v140, v154
	v_exp_f32_e32 v152, v207
	v_add_f32_e32 v154, v150, v154
	v_add_f32_e32 v154, v139, v154
	v_exp_f32_e32 v153, v210
	v_add_f32_e32 v154, v151, v154
	v_add_f32_e32 v154, v146, v154
	v_add_f32_e32 v154, v152, v154
	v_add_f32_e32 v154, v142, v154
	v_add_f32_e32 v154, v153, v154
	v_add_f32_e32 v154, v141, v154
	v_add_f32_e32 v226, v138, v154
	v_mov_b32_e32 v227, v226
	v_cvt_pk_bf16_f32 v130, v130, v211
	v_cvt_pk_bf16_f32 v131, v131, v212
	v_cvt_pk_bf16_f32 v132, v132, v213
	s_nop 1
	v_permlane32_swap_b32_e32 v226, v227
	v_cvt_pk_bf16_f32 v133, v133, v224
	v_permlane32_swap_b32_e32 v130, v132
	v_cvt_pk_bf16_f32 v154, v137, v228
	v_cvt_pk_bf16_f32 v155, v136, v229
	v_cvt_pk_bf16_f32 v156, v135, v230
	v_cvt_pk_bf16_f32 v157, v134, v231
	v_cvt_pk_bf16_f32 v218, v145, v147
	v_cvt_pk_bf16_f32 v219, v144, v148
	v_cvt_pk_bf16_f32 v220, v143, v149
	v_cvt_pk_bf16_f32 v221, v140, v150
	v_cvt_pk_bf16_f32 v228, v139, v151
	v_cvt_pk_bf16_f32 v229, v146, v152
	v_cvt_pk_bf16_f32 v230, v142, v153
	v_cvt_pk_bf16_f32 v231, v141, v138
	v_permlane32_swap_b32_e32 v131, v133
	v_permlane32_swap_b32_e32 v154, v156
	v_permlane32_swap_b32_e32 v155, v157
	v_permlane32_swap_b32_e32 v218, v220
	v_permlane32_swap_b32_e32 v219, v221
	v_permlane32_swap_b32_e32 v228, v230
	v_permlane32_swap_b32_e32 v229, v231
	s_add_i32 s38, s69, 1
	s_cmp_lt_u32 s38, s68
	s_cselect_b32 s14, 0, s68
	s_cselect_b32 s15, s25, s28
; #define SBAR() __builtin_amdgcn_sched_barrier(0)
; template <int OFF> __device__ __forceinline__ s16x4 tr_read(int vb) { s16x4 r; asm volatile("ds_read_b64_tr_b16 %0, %1 offset:%2" : "=&v"(r) : "v"(vb), "i"(OFF) : "memory"); return r; }
; template <int D0> __device__ __forceinline__ void pv_one(f32x16& od, int vb, bf16x8 pa0, bf16x8 pa1, bf16x8 pa2, bf16x8 pa3) {
;     const s16x4 l0 = tr_read<v_rd_off(D0, 0, 0)>(vb), h0 = tr_read<v_rd_off(D0, 0, 1)>(vb), l1 = tr_read<v_rd_off(D0, 1, 0)>(vb), h1 = tr_read<v_rd_off(D0, 1, 1)>(vb);
;     const s16x4 l2 = tr_read<v_rd_off(D0, 2, 0)>(vb), h2 = tr_read<v_rd_off(D0, 2, 1)>(vb), l3 = tr_read<v_rd_off(D0, 3, 0)>(vb), h3 = tr_read<v_rd_off(D0, 3, 1)>(vb);
;     asm volatile("s_waitcnt lgkmcnt(0)" ::: "memory"); SBAR();
;     ...
;     od = __builtin_amdgcn_mfma_f32_32x32x16_bf16(pa0, PK(l0, h0), od, 0, 0, 0);
;     od = __builtin_amdgcn_mfma_f32_32x32x16_bf16(pa1, PK(l1, h1), od, 0, 0, 0);
;     od = __builtin_amdgcn_mfma_f32_32x32x16_bf16(pa2, PK(l2, h2), od, 0, 0, 0);
;     od = __builtin_amdgcn_mfma_f32_32x32x16_bf16(pa3, PK(l3, h3), od, 0, 0, 0);
;     ...
; }
; __device__ __forceinline__ void pv_d0(f32x16* o, int vb, bf16x8 pa0, bf16x8 pa1, bf16x8 pa2, bf16x8 pa3) {
;     pv_one<0>(o[0], vb, pa0, pa1, pa2, pa3); pv_one<1>(o[1], vb, pa0, pa1, pa2, pa3); pv_one<2>(o[2], vb, pa0, pa1, pa2, pa3); pv_one<3>(o[3], vb, pa0, pa1, pa2, pa3);
; }
; __device__ __forceinline__ void partialSM(f32x16& p0, f32x16& p1, float& m_reg, float& mn, float& alpha, const float C, const float thr) {
;     float pmax = p0[0];
; #pragma unroll
;     for (int r = 1; r < 16; ++r) pmax = fmaxf(pmax, p0[r]);
; #pragma unroll
;     for (int r = 0; r < 16; ++r) pmax = fmaxf(pmax, p1[r]);
;     { auto rr = __builtin_amdgcn_permlane32_swap(__float_as_uint(pmax), __float_as_uint(pmax), false, false);
;       pmax = fmaxf(__uint_as_float(rr[0]), __uint_as_float(rr[1])); }
;     if (__builtin_expect(__all(pmax - m_reg <= thr), 1)) { mn = m_reg; alpha = 1.f; }
;     else { mn = fmaxf(m_reg, pmax); alpha = __builtin_amdgcn_exp2f((m_reg - mn) * C); m_reg = mn; }
;     const float mnC = -mn * C;
; #pragma unroll
;     for (int r = 0; r < 16; ++r) p0[r] = fmaf(p0[r], C, mnC);
; #pragma unroll
	s_lshl_b32 s14, s14, 6
	s_sub_i32 s14, s15, s14
	s_add_i32 s14, s37, s14
	s_add_i32 s14, s14, 64
	s_ashr_i32 s15, s14, 31
	v_lshl_add_u64 v[134:135], s[14:15], 0, v[174:175]
	v_lshl_add_u64 v[136:137], v[176:177], 0, s[14:15]
	v_lshlrev_b64 v[134:135], 12, v[134:135]
	v_lshlrev_b64 v[136:137], 12, v[136:137]
	v_lshl_add_u64 v[134:135], v[178:179], 0, v[134:135]
	v_lshl_add_u64 v[138:139], v[178:179], 0, v[136:137]
	v_mad_i64_i32 v[142:143], s[20:21], v164, s14, 0
	v_mad_i64_i32 v[146:147], s[20:21], v168, s14, 0
	v_mad_i64_i32 v[150:151], s[14:15], v172, s14, 0
	global_load_dwordx4 v[134:137], v[134:135], off offset:256
	s_nop 0
	global_load_dwordx4 v[138:141], v[138:139], off offset:256
	v_lshl_add_u64 v[142:143], v[142:143], 1, v[162:163]
	v_lshl_add_u64 v[146:147], v[146:147], 1, v[166:167]
	v_lshl_add_u64 v[150:151], v[150:151], 1, v[170:171]
	global_load_dwordx4 v[142:145], v[142:143], off
	s_nop 0
	global_load_dwordx4 v[146:149], v[146:147], off
	s_nop 0
	global_load_dwordx4 v[150:153], v[150:151], off
	ds_read_b64_tr_b16 v[232:233], v169 offset:0
	ds_read_b64_tr_b16 v[234:235], v169 offset:0x800
	ds_read_b64_tr_b16 v[236:237], v169 offset:0x1000
	ds_read_b64_tr_b16 v[238:239], v169 offset:0x1800
	ds_read_b64_tr_b16 v[240:241], v169 offset:0x2000
	ds_read_b64_tr_b16 v[242:243], v169 offset:0x2800
	ds_read_b64_tr_b16 v[244:245], v169 offset:0x3000
	ds_read_b64_tr_b16 v[246:247], v169 offset:0x3800
	s_waitcnt lgkmcnt(0)
	s_nop 0
	v_mfma_f32_32x32x16_bf16 v[48:63], v[130:133], v[232:235], v[48:63]
	ds_read_b64_tr_b16 v[232:233], v169 offset:0x200
	ds_read_b64_tr_b16 v[234:235], v169 offset:0xa00
	v_max_f32_e32 v248, v81, v81
	v_max_f32_e32 v249, v80, v80
	v_max_f32_e32 v248, v249, v248
	v_max3_f32 v248, v248, v82, v83
	v_max3_f32 v248, v248, v84, v85
	v_max3_f32 v248, v248, v86, v87
	v_mfma_f32_32x32x16_bf16 v[48:63], v[154:157], v[236:239], v[48:63]
	ds_read_b64_tr_b16 v[236:237], v169 offset:0x1200
	ds_read_b64_tr_b16 v[238:239], v169 offset:0x1a00
	v_max3_f32 v248, v248, v88, v89
	v_max3_f32 v248, v248, v90, v91
	v_max3_f32 v248, v248, v92, v93
	v_max3_f32 v248, v248, v94, v95
	v_max3_f32 v248, v248, v64, v65
	v_max3_f32 v248, v248, v66, v67
	v_mfma_f32_32x32x16_bf16 v[48:63], v[218:221], v[240:243], v[48:63]
	ds_read_b64_tr_b16 v[240:241], v169 offset:0x2200
	ds_read_b64_tr_b16 v[242:243], v169 offset:0x2a00
	v_max3_f32 v248, v248, v68, v69
	v_max3_f32 v248, v248, v70, v71
	v_max3_f32 v248, v248, v72, v73
	v_max3_f32 v248, v248, v74, v75
	v_max3_f32 v248, v248, v76, v77
	v_max3_f32 v248, v248, v78, v79
	v_mfma_f32_32x32x16_bf16 v[48:63], v[228:231], v[244:247], v[48:63]
	ds_read_b64_tr_b16 v[244:245], v169 offset:0x3200
	ds_read_b64_tr_b16 v[246:247], v169 offset:0x3a00
	v_mov_b32_e32 v249, v248
	s_nop 1
	v_permlane32_swap_b32_e32 v248, v249
	v_max_f32_e32 v249, v249, v249
	v_max_f32_e32 v248, v248, v248
	v_max_f32_e32 v248, v248, v249
	s_waitcnt lgkmcnt(6)
	v_mfma_f32_32x32x16_bf16 v[32:47], v[130:133], v[232:235], v[32:47]
	ds_read_b64_tr_b16 v[232:233], v169 offset:0x400
	ds_read_b64_tr_b16 v[234:235], v169 offset:0xc00
	v_sub_f32_e32 v249, v248, v204
	v_cmp_ge_f32_e32 vcc, s72, v249
	v_max_f32_e32 v249, v204, v204
	v_max_f32_e32 v248, v249, v248
	v_sub_f32_e32 v249, v204, v248
	v_mul_f32_e32 v249, 0x3dd53b94, v249
	s_waitcnt lgkmcnt(6)
	v_mfma_f32_32x32x16_bf16 v[32:47], v[154:157], v[236:239], v[32:47]
	ds_read_b64_tr_b16 v[236:237], v169 offset:0x1400
	ds_read_b64_tr_b16 v[238:239], v169 offset:0x1c00
	v_exp_f32_e32 v249, v249
	s_cmp_eq_u64 vcc, exec
	s_cselect_b64 s[14:15], -1, 0
	v_cndmask_b32_e64 v224, v249, 1.0, s[14:15]
	v_cmp_gt_f32_e32 vcc, 1.0, v224
	s_waitcnt lgkmcnt(6)
	v_mfma_f32_32x32x16_bf16 v[32:47], v[218:221], v[240:243], v[32:47]
	ds_read_b64_tr_b16 v[240:241], v169 offset:0x2400
	ds_read_b64_tr_b16 v[242:243], v169 offset:0x2c00
	v_cndmask_b32_e64 v251, v248, v204, s[14:15]
	v_mul_f32_e32 v249, 0xbdd53b94, v251
	v_fmamk_f32 v80, v80, 0x3dd53b94, v249
	v_fmamk_f32 v81, v81, 0x3dd53b94, v249
	s_waitcnt lgkmcnt(6)
	v_mfma_f32_32x32x16_bf16 v[32:47], v[228:231], v[244:247], v[32:47]
	ds_read_b64_tr_b16 v[244:245], v169 offset:0x3400
	ds_read_b64_tr_b16 v[246:247], v169 offset:0x3c00
	v_fmamk_f32 v82, v82, 0x3dd53b94, v249
	v_fmamk_f32 v83, v83, 0x3dd53b94, v249
	v_fmamk_f32 v84, v84, 0x3dd53b94, v249
	v_fmamk_f32 v85, v85, 0x3dd53b94, v249
	s_waitcnt lgkmcnt(6)
	v_mfma_f32_32x32x16_bf16 v[16:31], v[130:133], v[232:235], v[16:31]
	ds_read_b64_tr_b16 v[232:233], v169 offset:0x600
	ds_read_b64_tr_b16 v[234:235], v169 offset:0xe00
	v_fmamk_f32 v86, v86, 0x3dd53b94, v249
	v_fmamk_f32 v87, v87, 0x3dd53b94, v249
	v_fmamk_f32 v88, v88, 0x3dd53b94, v249
	v_fmamk_f32 v89, v89, 0x3dd53b94, v249
	s_waitcnt lgkmcnt(6)
	v_mfma_f32_32x32x16_bf16 v[16:31], v[154:157], v[236:239], v[16:31]
	ds_read_b64_tr_b16 v[236:237], v169 offset:0x1600
	ds_read_b64_tr_b16 v[238:239], v169 offset:0x1e00
	v_fmamk_f32 v90, v90, 0x3dd53b94, v249
	v_fmamk_f32 v91, v91, 0x3dd53b94, v249
	v_fmamk_f32 v92, v92, 0x3dd53b94, v249
	v_fmamk_f32 v93, v93, 0x3dd53b94, v249
	s_waitcnt lgkmcnt(6)
	v_mfma_f32_32x32x16_bf16 v[16:31], v[218:221], v[240:243], v[16:31]
	ds_read_b64_tr_b16 v[240:241], v169 offset:0x2600
	ds_read_b64_tr_b16 v[242:243], v169 offset:0x2e00
	v_fmamk_f32 v94, v94, 0x3dd53b94, v249
	s_waitcnt lgkmcnt(6)
	v_mfma_f32_32x32x16_bf16 v[16:31], v[228:231], v[244:247], v[16:31]
	ds_read_b64_tr_b16 v[244:245], v169 offset:0x3600
	ds_read_b64_tr_b16 v[246:247], v169 offset:0x3e00
	s_waitcnt lgkmcnt(6)
	v_mfma_f32_32x32x16_bf16 v[0:15], v[130:133], v[232:235], v[0:15]
	s_waitcnt lgkmcnt(4)
	v_mfma_f32_32x32x16_bf16 v[0:15], v[154:157], v[236:239], v[0:15]
	s_waitcnt lgkmcnt(2)
	v_mfma_f32_32x32x16_bf16 v[0:15], v[218:221], v[240:243], v[0:15]
	s_waitcnt lgkmcnt(0)
	v_mfma_f32_32x32x16_bf16 v[0:15], v[228:231], v[244:247], v[0:15]
	s_barrier
	s_waitcnt vmcnt(4)
	ds_write_b128 v186, v[134:137] offset:16384
	s_waitcnt vmcnt(3)
	ds_write_b128 v188, v[138:141] offset:16384
	s_waitcnt vmcnt(2)
	ds_write_b128 v194, v[142:145] offset:57344
	s_waitcnt vmcnt(1)
	ds_write_b128 v196, v[146:149] offset:57344
	s_waitcnt vmcnt(0)
	ds_write_b128 v198, v[150:153] offset:57344
	s_cbranch_vccz .LBB0_227
	s_and_saveexec_b64 s[20:21], s[12:13]
	ds_write_b32 v165, v224 offset:128
	s_or_b64 exec, exec, s[20:21]
	s_waitcnt lgkmcnt(0)
	v_add_u32_e32 v131, v161, v96
	ds_read_b128 v[132:135], v131 offset:224
	ds_read_b128 v[136:139], v131 offset:192
	ds_read_b128 v[140:143], v131 offset:160
	ds_read_b128 v[144:147], v131 offset:128
	s_waitcnt lgkmcnt(3)
	v_pk_mul_f32 v[60:61], v[60:61], v[132:133]
	s_waitcnt lgkmcnt(2)
	v_pk_mul_f32 v[56:57], v[56:57], v[136:137]
	s_waitcnt lgkmcnt(1)
	v_pk_mul_f32 v[52:53], v[52:53], v[140:141]
	v_pk_mul_f32 v[62:63], v[62:63], v[134:135]
	v_pk_mul_f32 v[58:59], v[58:59], v[138:139]
	v_pk_mul_f32 v[54:55], v[54:55], v[142:143]
	s_waitcnt lgkmcnt(0)
	v_pk_mul_f32 v[50:51], v[50:51], v[146:147]
	v_pk_mul_f32 v[48:49], v[48:49], v[144:145]
	v_pk_mul_f32 v[44:45], v[44:45], v[132:133]
	v_pk_mul_f32 v[40:41], v[40:41], v[136:137]
	v_pk_mul_f32 v[36:37], v[36:37], v[140:141]
	v_pk_mul_f32 v[46:47], v[46:47], v[134:135]
	v_pk_mul_f32 v[42:43], v[42:43], v[138:139]
	v_pk_mul_f32 v[38:39], v[38:39], v[142:143]
	v_pk_mul_f32 v[34:35], v[34:35], v[146:147]
	v_pk_mul_f32 v[32:33], v[32:33], v[144:145]
	v_pk_mul_f32 v[28:29], v[28:29], v[132:133]
	v_pk_mul_f32 v[24:25], v[24:25], v[136:137]
	v_pk_mul_f32 v[20:21], v[20:21], v[140:141]
	v_pk_mul_f32 v[30:31], v[30:31], v[134:135]
	v_pk_mul_f32 v[26:27], v[26:27], v[138:139]
	v_pk_mul_f32 v[22:23], v[22:23], v[142:143]
	v_pk_mul_f32 v[18:19], v[18:19], v[146:147]
	v_pk_mul_f32 v[16:17], v[16:17], v[144:145]
	v_pk_mul_f32 v[12:13], v[12:13], v[132:133]
	v_pk_mul_f32 v[8:9], v[8:9], v[136:137]
	v_pk_mul_f32 v[4:5], v[4:5], v[140:141]
	v_pk_mul_f32 v[14:15], v[14:15], v[134:135]
	v_pk_mul_f32 v[10:11], v[10:11], v[138:139]
	v_pk_mul_f32 v[6:7], v[6:7], v[142:143]
	v_pk_mul_f32 v[2:3], v[2:3], v[146:147]
	v_pk_mul_f32 v[0:1], v[0:1], v[144:145]
